# adds P1 V-tile epilogue stores widened 8B->16B (32->16, addresses traced per store, emitted from the m3 store address with negative offsets), on top of v46
# speedup vs baseline: 1.0619x; 1.0067x over previous
.LBB0_146:
	s_or_b64 exec, exec, s[8:9]
	s_lshl_b32 s0, s94, 8
	v_lshl_or_b32 v132, s96, 8, v1
	v_mov_b32_e32 v130, v163
	s_waitcnt vmcnt(0)
	s_barrier
	v_mbcnt_lo_u32_b32 v244, -1, 0
	v_mbcnt_hi_u32_b32 v244, -1, v244
	v_bfe_u32 v244, v244, 4, 1
	v_mul_u32_u24_e32 v244, 24, v244
	v_mov_b32_e32 v245, 0
	s_addk_i32 s0, 0xf400
	v_add_u32_e32 v133, s0, v130
	v_ashrrev_i32_e32 v130, 2, v132
	v_and_b32_e32 v130, 0xfffffc00, v130
	v_add_u32_e32 v130, v130, v133
	v_cvt_pk_bf16_f32 v166, v114, v115
	v_cvt_pk_bf16_f32 v167, v116, v117
	v_add_u32_e32 v116, 16, v130
	v_ashrrev_i32_e32 v117, 31, v116
	v_and_b32_e32 v134, 0xfff, v132
	v_lshlrev_b64 v[116:117], 13, v[116:117]
	v_lshlrev_b32_e32 v164, 1, v134
	v_lshl_add_u64 v[116:117], s[74:75], 0, v[116:117]
	v_lshl_add_u64 v[116:117], v[116:117], 0, v[164:165]
	v_add_u32_e32 v114, 0x80, v130
	v_ashrrev_i32_e32 v115, 31, v114
	v_lshlrev_b64 v[114:115], 13, v[114:115]
	v_lshl_add_u64 v[114:115], s[74:75], 0, v[114:115]
	v_cvt_pk_bf16_f32 v174, v122, v123
	v_cvt_pk_bf16_f32 v175, v124, v125
	v_lshl_add_u64 v[114:115], v[114:115], 0, v[164:165]
	v_add_u32_e32 v116, 0x90, v130
	v_ashrrev_i32_e32 v117, 31, v116
	v_lshlrev_b64 v[116:117], 13, v[116:117]
	v_lshl_add_u64 v[116:117], s[74:75], 0, v[116:117]
	v_cvt_pk_bf16_f32 v182, v118, v119
	v_cvt_pk_bf16_f32 v183, v120, v121
	v_lshl_add_u64 v[116:117], v[116:117], 0, v[164:165]
	v_add_u32_e32 v114, 16, v132
	v_and_b32_e32 v116, 0xfff, v114
	v_ashrrev_i32_e32 v114, 2, v114
	v_and_b32_e32 v114, 0xfffffc00, v114
	v_add_u32_e32 v114, v114, v133
	v_ashrrev_i32_e32 v131, 31, v130
	v_cvt_pk_bf16_f32 v168, v98, v99
	v_cvt_pk_bf16_f32 v169, v100, v101
	v_add_u32_e32 v100, 16, v114
	v_cvt_pk_bf16_f32 v190, v126, v127
	v_cvt_pk_bf16_f32 v191, v128, v129
	v_lshlrev_b64 v[128:129], 13, v[130:131]
	v_ashrrev_i32_e32 v101, 31, v100
	v_lshl_add_u64 v[128:129], s[74:75], 0, v[128:129]
	v_lshlrev_b64 v[100:101], 13, v[100:101]
	v_lshl_add_u64 v[128:129], v[128:129], 0, v[164:165]
	v_lshlrev_b32_e32 v164, 1, v116
	v_lshl_add_u64 v[100:101], s[74:75], 0, v[100:101]
	v_lshl_add_u64 v[100:101], v[100:101], 0, v[164:165]
	v_add_u32_e32 v98, 0x80, v114
	v_ashrrev_i32_e32 v99, 31, v98
	v_lshlrev_b64 v[98:99], 13, v[98:99]
	v_lshl_add_u64 v[98:99], s[74:75], 0, v[98:99]
	v_cvt_pk_bf16_f32 v176, v106, v107
	v_cvt_pk_bf16_f32 v177, v108, v109
	v_lshl_add_u64 v[98:99], v[98:99], 0, v[164:165]
	v_add_u32_e32 v100, 0x90, v114
	v_ashrrev_i32_e32 v101, 31, v100
	v_lshlrev_b64 v[100:101], 13, v[100:101]
	v_lshl_add_u64 v[100:101], s[74:75], 0, v[100:101]
	v_cvt_pk_bf16_f32 v184, v102, v103
	v_cvt_pk_bf16_f32 v185, v104, v105
	v_lshl_add_u64 v[100:101], v[100:101], 0, v[164:165]
	v_add_u32_e32 v98, 32, v132
	v_and_b32_e32 v100, 0xfff, v98
	v_ashrrev_i32_e32 v98, 2, v98
	v_and_b32_e32 v98, 0xfffffc00, v98
	v_add_u32_e32 v98, v98, v133
	v_ashrrev_i32_e32 v115, 31, v114
	v_cvt_pk_bf16_f32 v170, v82, v83
	v_cvt_pk_bf16_f32 v171, v84, v85
	v_add_u32_e32 v84, 16, v98
	v_cvt_pk_bf16_f32 v192, v110, v111
	v_cvt_pk_bf16_f32 v193, v112, v113
	v_lshlrev_b64 v[112:113], 13, v[114:115]
	v_ashrrev_i32_e32 v85, 31, v84
	v_lshl_add_u64 v[112:113], s[74:75], 0, v[112:113]
	v_lshlrev_b64 v[84:85], 13, v[84:85]
	v_lshl_add_u64 v[112:113], v[112:113], 0, v[164:165]
	v_lshlrev_b32_e32 v164, 1, v100
	v_lshl_add_u64 v[84:85], s[74:75], 0, v[84:85]
	v_lshl_add_u64 v[84:85], v[84:85], 0, v[164:165]
	v_add_u32_e32 v82, 0x80, v98
	v_ashrrev_i32_e32 v83, 31, v82
	v_lshlrev_b64 v[82:83], 13, v[82:83]
	v_lshl_add_u64 v[82:83], s[74:75], 0, v[82:83]
	v_cvt_pk_bf16_f32 v178, v90, v91
	v_cvt_pk_bf16_f32 v179, v92, v93
	v_lshl_add_u64 v[82:83], v[82:83], 0, v[164:165]
	v_add_u32_e32 v84, 0x90, v98
	v_ashrrev_i32_e32 v85, 31, v84
	v_lshlrev_b64 v[84:85], 13, v[84:85]
	v_lshl_add_u64 v[84:85], s[74:75], 0, v[84:85]
	v_cvt_pk_bf16_f32 v186, v86, v87
	v_cvt_pk_bf16_f32 v187, v88, v89
	v_lshl_add_u64 v[84:85], v[84:85], 0, v[164:165]
	v_add_u32_e32 v82, 48, v132
	v_and_b32_e32 v84, 0xfff, v82
	v_ashrrev_i32_e32 v82, 2, v82
	v_and_b32_e32 v82, 0xfffffc00, v82
	v_add_u32_e32 v82, v82, v133
	v_ashrrev_i32_e32 v99, 31, v98
	v_cvt_pk_bf16_f32 v172, v62, v63
	v_cvt_pk_bf16_f32 v173, v64, v65
	v_add_u32_e32 v64, 16, v82
	v_cvt_pk_bf16_f32 v194, v94, v95
	v_cvt_pk_bf16_f32 v195, v96, v97
	v_lshlrev_b64 v[96:97], 13, v[98:99]
	v_ashrrev_i32_e32 v65, 31, v64
	v_lshl_add_u64 v[96:97], s[74:75], 0, v[96:97]
	v_lshlrev_b64 v[64:65], 13, v[64:65]
	v_lshl_add_u64 v[96:97], v[96:97], 0, v[164:165]
	v_lshlrev_b32_e32 v164, 1, v84
	v_lshl_add_u64 v[64:65], s[74:75], 0, v[64:65]
	v_lshl_add_u64 v[64:65], v[64:65], 0, v[164:165]
	s_nop 1
	v_permlane16_swap_b32_e32 v166, v168
	v_permlane16_swap_b32_e32 v167, v169
	v_permlane16_swap_b32_e32 v170, v172
	v_permlane16_swap_b32_e32 v171, v173
	v_lshl_add_u64 v[240:241], v[64:65], 0, v[244:245]
	global_store_dwordx4 v[240:241], v[166:169], off offset:-96
	global_store_dwordx4 v[240:241], v[170:173], off offset:-32
	v_add_u32_e32 v62, 0x80, v82
	v_ashrrev_i32_e32 v63, 31, v62
	v_lshlrev_b64 v[62:63], 13, v[62:63]
	v_lshl_add_u64 v[62:63], s[74:75], 0, v[62:63]
	v_cvt_pk_bf16_f32 v180, v74, v75
	v_cvt_pk_bf16_f32 v181, v76, v77
	v_lshl_add_u64 v[62:63], v[62:63], 0, v[164:165]
	s_nop 1
	v_permlane16_swap_b32_e32 v174, v176
	v_permlane16_swap_b32_e32 v175, v177
	v_permlane16_swap_b32_e32 v178, v180
	v_permlane16_swap_b32_e32 v179, v181
	v_lshl_add_u64 v[240:241], v[62:63], 0, v[244:245]
	global_store_dwordx4 v[240:241], v[174:177], off offset:-96
	global_store_dwordx4 v[240:241], v[178:181], off offset:-32
	v_add_u32_e32 v64, 0x90, v82
	v_ashrrev_i32_e32 v65, 31, v64
	v_lshlrev_b64 v[64:65], 13, v[64:65]
	v_lshl_add_u64 v[64:65], s[74:75], 0, v[64:65]
	v_cvt_pk_bf16_f32 v188, v70, v71
	v_cvt_pk_bf16_f32 v189, v72, v73
	v_lshl_add_u64 v[64:65], v[64:65], 0, v[164:165]
	s_nop 1
	v_permlane16_swap_b32_e32 v182, v184
	v_permlane16_swap_b32_e32 v183, v185
	v_permlane16_swap_b32_e32 v186, v188
	v_permlane16_swap_b32_e32 v187, v189
	v_lshl_add_u64 v[240:241], v[64:65], 0, v[244:245]
	global_store_dwordx4 v[240:241], v[182:185], off offset:-96
	global_store_dwordx4 v[240:241], v[186:189], off offset:-32
	v_add_u32_e32 v62, 0x80, v132
	v_and_b32_e32 v70, 0xfff, v62
	v_ashrrev_i32_e32 v62, 2, v62
	v_and_b32_e32 v62, 0xfffffc00, v62
	v_add_u32_e32 v62, v62, v133
	v_ashrrev_i32_e32 v83, 31, v82
	v_cvt_pk_bf16_f32 v166, v50, v51
	v_cvt_pk_bf16_f32 v167, v52, v53
	v_add_u32_e32 v52, 0x90, v62
	v_cvt_pk_bf16_f32 v196, v78, v79
	v_cvt_pk_bf16_f32 v197, v80, v81
	v_lshlrev_b64 v[80:81], 13, v[82:83]
	v_ashrrev_i32_e32 v53, 31, v52
	v_lshl_add_u64 v[80:81], s[74:75], 0, v[80:81]
	v_lshlrev_b64 v[52:53], 13, v[52:53]
	v_lshl_add_u64 v[80:81], v[80:81], 0, v[164:165]
	v_lshlrev_b32_e32 v164, 1, v70
	v_cvt_pk_bf16_f32 v174, v54, v55
	v_cvt_pk_bf16_f32 v175, v56, v57
	v_add_u32_e32 v56, 16, v62
	v_lshl_add_u64 v[52:53], s[74:75], 0, v[52:53]
	v_ashrrev_i32_e32 v57, 31, v56
	v_lshl_add_u64 v[52:53], v[52:53], 0, v[164:165]
	s_nop 1
	v_permlane16_swap_b32_e32 v190, v192
	v_permlane16_swap_b32_e32 v191, v193
	v_permlane16_swap_b32_e32 v194, v196
	v_permlane16_swap_b32_e32 v195, v197
	v_lshl_add_u64 v[240:241], v[80:81], 0, v[244:245]
	global_store_dwordx4 v[240:241], v[190:193], off offset:-96
	global_store_dwordx4 v[240:241], v[194:197], off offset:-32
	v_lshlrev_b64 v[56:57], 13, v[56:57]
	v_add_u32_e32 v50, 0x90, v132
	v_lshl_add_u64 v[56:57], s[74:75], 0, v[56:57]
	v_and_b32_e32 v52, 0xfff, v50
	v_ashrrev_i32_e32 v50, 2, v50
	v_lshl_add_u64 v[56:57], v[56:57], 0, v[164:165]
	v_and_b32_e32 v50, 0xfffffc00, v50
	v_add_u32_e32 v54, 0x80, v62
	v_add_u32_e32 v50, v50, v133
	v_ashrrev_i32_e32 v63, 31, v62
	v_ashrrev_i32_e32 v55, 31, v54
	v_cvt_pk_bf16_f32 v168, v34, v35
	v_cvt_pk_bf16_f32 v169, v36, v37
	v_add_u32_e32 v36, 0x90, v50
	v_cvt_pk_bf16_f32 v182, v66, v67
	v_lshlrev_b64 v[66:67], 13, v[62:63]
	v_lshlrev_b64 v[54:55], 13, v[54:55]
	v_ashrrev_i32_e32 v37, 31, v36
	v_lshl_add_u64 v[66:67], s[74:75], 0, v[66:67]
	v_lshl_add_u64 v[54:55], s[74:75], 0, v[54:55]
	v_lshlrev_b64 v[36:37], 13, v[36:37]
	v_lshl_add_u64 v[66:67], v[66:67], 0, v[164:165]
	v_lshl_add_u64 v[54:55], v[54:55], 0, v[164:165]
	v_lshlrev_b32_e32 v164, 1, v52
	v_cvt_pk_bf16_f32 v176, v38, v39
	v_cvt_pk_bf16_f32 v177, v40, v41
	v_add_u32_e32 v40, 16, v50
	v_lshl_add_u64 v[36:37], s[74:75], 0, v[36:37]
	v_cvt_pk_bf16_f32 v183, v68, v69
	v_cvt_pk_bf16_f32 v190, v58, v59
	v_cvt_pk_bf16_f32 v191, v60, v61
	v_ashrrev_i32_e32 v41, 31, v40
	v_lshl_add_u64 v[36:37], v[36:37], 0, v[164:165]
	v_lshlrev_b64 v[40:41], 13, v[40:41]
	v_add_u32_e32 v34, 0xa0, v132
	v_lshl_add_u64 v[40:41], s[74:75], 0, v[40:41]
	v_and_b32_e32 v36, 0xfff, v34
	v_ashrrev_i32_e32 v34, 2, v34
	v_lshl_add_u64 v[40:41], v[40:41], 0, v[164:165]
	v_and_b32_e32 v34, 0xfffffc00, v34
	v_add_u32_e32 v38, 0x80, v50
	v_add_u32_e32 v34, v34, v133
	v_ashrrev_i32_e32 v51, 31, v50
	v_ashrrev_i32_e32 v39, 31, v38
	v_cvt_pk_bf16_f32 v170, v18, v19
	v_cvt_pk_bf16_f32 v171, v20, v21
	v_add_u32_e32 v20, 0x90, v34
	v_cvt_pk_bf16_f32 v184, v46, v47
	v_cvt_pk_bf16_f32 v185, v48, v49
	v_lshlrev_b64 v[48:49], 13, v[50:51]
	v_lshlrev_b64 v[38:39], 13, v[38:39]
	v_ashrrev_i32_e32 v21, 31, v20
	v_lshl_add_u64 v[48:49], s[74:75], 0, v[48:49]
	v_lshl_add_u64 v[38:39], s[74:75], 0, v[38:39]
	v_lshlrev_b64 v[20:21], 13, v[20:21]
	v_lshl_add_u64 v[48:49], v[48:49], 0, v[164:165]
	v_lshl_add_u64 v[38:39], v[38:39], 0, v[164:165]
	v_lshlrev_b32_e32 v164, 1, v36
	v_cvt_pk_bf16_f32 v178, v22, v23
	v_cvt_pk_bf16_f32 v179, v24, v25
	v_add_u32_e32 v24, 16, v34
	v_lshl_add_u64 v[20:21], s[74:75], 0, v[20:21]
	v_cvt_pk_bf16_f32 v192, v42, v43
	v_cvt_pk_bf16_f32 v193, v44, v45
	v_ashrrev_i32_e32 v25, 31, v24
	v_lshl_add_u64 v[20:21], v[20:21], 0, v[164:165]
	v_lshlrev_b64 v[24:25], 13, v[24:25]
	v_add_u32_e32 v18, 0xb0, v132
	v_lshl_add_u64 v[24:25], s[74:75], 0, v[24:25]
	v_and_b32_e32 v20, 0xfff, v18
	v_ashrrev_i32_e32 v18, 2, v18
	v_lshl_add_u64 v[24:25], v[24:25], 0, v[164:165]
	v_and_b32_e32 v18, 0xfffffc00, v18
	v_add_u32_e32 v22, 0x80, v34
	v_add_u32_e32 v18, v18, v133
	v_ashrrev_i32_e32 v35, 31, v34
	v_ashrrev_i32_e32 v23, 31, v22
	v_cvt_pk_bf16_f32 v180, v6, v7
	v_cvt_pk_bf16_f32 v181, v8, v9
	v_add_u32_e32 v8, 16, v18
	v_cvt_pk_bf16_f32 v186, v30, v31
	v_cvt_pk_bf16_f32 v187, v32, v33
	v_lshlrev_b64 v[32:33], 13, v[34:35]
	v_lshlrev_b64 v[22:23], 13, v[22:23]
	v_ashrrev_i32_e32 v9, 31, v8
	v_lshl_add_u64 v[32:33], s[74:75], 0, v[32:33]
	v_lshl_add_u64 v[22:23], s[74:75], 0, v[22:23]
	v_lshlrev_b64 v[8:9], 13, v[8:9]
	v_lshl_add_u64 v[32:33], v[32:33], 0, v[164:165]
	v_lshl_add_u64 v[22:23], v[22:23], 0, v[164:165]
	v_lshlrev_b32_e32 v164, 1, v20
	v_lshl_add_u64 v[8:9], s[74:75], 0, v[8:9]
	v_cvt_pk_bf16_f32 v194, v26, v27
	v_cvt_pk_bf16_f32 v195, v28, v29
	v_lshl_add_u64 v[8:9], v[8:9], 0, v[164:165]
	s_nop 1
	v_permlane16_swap_b32_e32 v174, v176
	v_permlane16_swap_b32_e32 v175, v177
	v_permlane16_swap_b32_e32 v178, v180
	v_permlane16_swap_b32_e32 v179, v181
	v_lshl_add_u64 v[240:241], v[8:9], 0, v[244:245]
	global_store_dwordx4 v[240:241], v[174:177], off offset:-96
	global_store_dwordx4 v[240:241], v[178:181], off offset:-32
	v_add_u32_e32 v6, 0x80, v18
	v_cvt_pk_bf16_f32 v172, v2, v3
	v_cvt_pk_bf16_f32 v173, v4, v5
	v_add_u32_e32 v4, 0x90, v18
	v_ashrrev_i32_e32 v19, 31, v18
	v_ashrrev_i32_e32 v7, 31, v6
	v_ashrrev_i32_e32 v5, 31, v4
	v_cvt_pk_bf16_f32 v188, v14, v15
	v_cvt_pk_bf16_f32 v189, v16, v17
	v_lshlrev_b64 v[16:17], 13, v[18:19]
	v_lshlrev_b64 v[6:7], 13, v[6:7]
	v_lshlrev_b64 v[4:5], 13, v[4:5]
	v_lshl_add_u64 v[16:17], s[74:75], 0, v[16:17]
	v_lshl_add_u64 v[6:7], s[74:75], 0, v[6:7]
	v_lshl_add_u64 v[4:5], s[74:75], 0, v[4:5]
	v_lshl_add_u64 v[16:17], v[16:17], 0, v[164:165]
	v_cvt_pk_bf16_f32 v196, v10, v11
	v_cvt_pk_bf16_f32 v197, v12, v13
	v_lshl_add_u64 v[6:7], v[6:7], 0, v[164:165]
	v_lshl_add_u64 v[4:5], v[4:5], 0, v[164:165]
	s_nop 1
	v_permlane16_swap_b32_e32 v182, v184
	v_permlane16_swap_b32_e32 v183, v185
	v_permlane16_swap_b32_e32 v186, v188
	v_permlane16_swap_b32_e32 v187, v189
	v_lshl_add_u64 v[240:241], v[16:17], 0, v[244:245]
	global_store_dwordx4 v[240:241], v[182:185], off offset:-96
	global_store_dwordx4 v[240:241], v[186:189], off offset:-32
	s_nop 1
	v_permlane16_swap_b32_e32 v190, v192
	v_permlane16_swap_b32_e32 v191, v193
	v_permlane16_swap_b32_e32 v194, v196
	v_permlane16_swap_b32_e32 v195, v197
	v_lshl_add_u64 v[240:241], v[6:7], 0, v[244:245]
	global_store_dwordx4 v[240:241], v[190:193], off offset:-96
	global_store_dwordx4 v[240:241], v[194:197], off offset:-32
	s_nop 1
	v_permlane16_swap_b32_e32 v166, v168
	v_permlane16_swap_b32_e32 v167, v169
	v_permlane16_swap_b32_e32 v170, v172
	v_permlane16_swap_b32_e32 v171, v173
	v_lshl_add_u64 v[240:241], v[4:5], 0, v[244:245]
	global_store_dwordx4 v[240:241], v[166:169], off offset:-96
	global_store_dwordx4 v[240:241], v[170:173], off offset:-32
